# side_gemm1: row-scale and bias loads of the softplus epilogue issued before the split-K main part
# speedup vs baseline: 1.0051x; 1.0005x over previous
; #define GAS __attribute__((address_space(1)))
; __device__ __forceinline__ gws_t launder_s(const void* p0) { unsigned char* p = (unsigned char*)p0; asm volatile("" : "+s"(p)); return (gws_t)p; }
; __device__ __forceinline__ int launder_v(int v) { asm volatile("" : "+v"(v)); return v; }
; __device__ __forceinline__ int grid_x() { int g = (int)gridDim.x; asm volatile("" : "+s"(g)); return g; }
; __device__ __forceinline__ void side_gemm1(const Params& P, int seg) {
;     gws_t ws = launder_s(P.ws);
;     const int tidl = launder_v(threadIdx.x), lane = tidl & 63, gw = blockIdx.x * 8 + (tidl >> 6), NGW = grid_x() * 8;
;     const GAS bf16* xb = (const GAS bf16*)(ws + WS_XB) + (size_t)seg * RSB * DM; const GAS float* rstd1 = (const GAS float*)(ws + WS_RSTD1) + (size_t)seg * RSB;
;     const GAS bf16* Wt = (const GAS bf16*)(ws + WS_WIN); GAS float* dtv = (GAS float*)(ws + WS_DT); GAS bf16* proj = (GAS bf16*)(ws + WS_PROJ);
;     const int nrt = RS / 16 + (seg == 0 ? 1 : 0);
;     for (int it = gw; it < nrt * 4; it += NGW) { const int rt = it >> 2, r0 = (rt < RS / 16) ? rt * 16 : RS + 48;
;         skinny_tile(xb + (size_t)r0 * DM, DM, Wt + (size_t)NPROJ * DM, DM, (it & 3) * 16, lane, [&](int row, int j, int col, float v) {
;             const float t = v * rstd1[r0 + row] + P.dt_bias[col]; dtv[(size_t)(r0 + row) * 64 + col] = (t > 20.f) ? t : log1pf(__expf(t)); }); }
.Lsg1_new:
	s_mov_b32 s100, 0
	v_or_b32_e32 v16, v16, v29
	v_lshlrev_b32_e32 v174, 2, v17
	v_ashrrev_i32_e32 v17, 31, v16
	v_lshl_add_u64 v[18:19], v[16:17], 2, s[14:15]
	v_mov_b64_e32 v[248:249], v[18:19]
	global_load_dword v243, v[248:249], off
	global_load_dword v244, v174, s[44:45]
	global_load_dword v245, v[248:249], off offset:4
	global_load_dword v246, v[248:249], off offset:8
	global_load_dword v247, v[248:249], off offset:12
	v_lshrrev_b32_e32 v116, 6, v172
	v_and_b32_e32 v117, 3, v116
	v_lshlrev_b32_e32 v18, 9, v116
	v_mov_b32_e32 v19, 0
	v_lshl_add_u64 v[232:233], v[4:5], 0, v[18:19]
	v_cmp_gt_u32_e64 s[54:55], 4, v116
	v_mov_b32_e32 v222, 0x10000
	v_mov_b32_e32 v220, 0xffff0000
	s_nop 1
	v_cndmask_b32_e64 v220, v220, v222, s[54:55]
	v_ashrrev_i32_e32 v221, 31, v220
	v_lshl_add_u64 v[234:235], v[232:233], 0, v[220:221]
	v_and_b32_e32 v236, 48, v172
	v_lshl_add_u32 v236, v28, 12, v236
	v_add_u32_e32 v236, v236, v18
	s_add_u32 s46, s40, 0x5000000
	s_addc_u32 s47, s41, 0
	s_add_u32 s48, s46, 0x10000
	s_addc_u32 s49, s47, 0
	s_add_u32 s50, s46, 0x20000
	s_addc_u32 s51, s47, 0
	s_add_u32 s52, s46, 0x30000
	s_addc_u32 s53, s47, 0
	global_load_dwordx4 v[68:71], v[232:233], off
	global_load_dwordx4 v[76:79], v[234:235], off
	global_load_dwordx4 v[72:75], v[232:233], off offset:64
	global_load_dwordx4 v[80:83], v[234:235], off offset:64
	global_load_dwordx4 v[84:87], v236, s[46:47]
	global_load_dwordx4 v[88:91], v236, s[46:47] offset:64
	global_load_dwordx4 v[92:95], v236, s[48:49]
	global_load_dwordx4 v[96:99], v236, s[48:49] offset:64
	global_load_dwordx4 v[100:103], v236, s[50:51]
	global_load_dwordx4 v[104:107], v236, s[50:51] offset:64
	global_load_dwordx4 v[108:111], v236, s[52:53]
	global_load_dwordx4 v[112:115], v236, s[52:53] offset:64
	global_load_dwordx4 v[120:123], v[232:233], off offset:128
	global_load_dwordx4 v[128:131], v[234:235], off offset:128
	global_load_dwordx4 v[124:127], v[232:233], off offset:192
	global_load_dwordx4 v[132:135], v[234:235], off offset:192
	global_load_dwordx4 v[136:139], v236, s[46:47] offset:128
	global_load_dwordx4 v[140:143], v236, s[46:47] offset:192
	global_load_dwordx4 v[144:147], v236, s[48:49] offset:128
	global_load_dwordx4 v[148:151], v236, s[48:49] offset:192
	global_load_dwordx4 v[152:155], v236, s[50:51] offset:128
	global_load_dwordx4 v[156:159], v236, s[50:51] offset:192
	global_load_dwordx4 v[160:163], v236, s[52:53] offset:128
	global_load_dwordx4 v[164:167], v236, s[52:53] offset:192
	global_load_dwordx4 v[184:187], v[232:233], off offset:256
	global_load_dwordx4 v[192:195], v[234:235], off offset:256
	global_load_dwordx4 v[188:191], v[232:233], off offset:320
	global_load_dwordx4 v[196:199], v[234:235], off offset:320
	global_load_dwordx4 v[200:203], v236, s[46:47] offset:256
	global_load_dwordx4 v[204:207], v236, s[46:47] offset:320
	global_load_dwordx4 v[208:211], v236, s[48:49] offset:256
	global_load_dwordx4 v[212:215], v236, s[48:49] offset:320
	global_load_dwordx4 v[216:219], v236, s[50:51] offset:256
	global_load_dwordx4 v[220:223], v236, s[50:51] offset:320
	global_load_dwordx4 v[224:227], v236, s[52:53] offset:256
	global_load_dwordx4 v[228:231], v236, s[52:53] offset:320
	s_waitcnt vmcnt(24)
	v_mfma_f32_16x16x32_bf16 v[36:39], v[68:71], v[84:87], 0
	v_mfma_f32_16x16x32_bf16 v[40:43], v[68:71], v[92:95], 0
	v_mfma_f32_16x16x32_bf16 v[44:47], v[68:71], v[100:103], 0
	v_mfma_f32_16x16x32_bf16 v[48:51], v[68:71], v[108:111], 0
	v_mfma_f32_16x16x32_bf16 v[52:55], v[76:79], v[84:87], 0
	v_mfma_f32_16x16x32_bf16 v[56:59], v[76:79], v[92:95], 0
	v_mfma_f32_16x16x32_bf16 v[60:63], v[76:79], v[100:103], 0
	v_mfma_f32_16x16x32_bf16 v[64:67], v[76:79], v[108:111], 0
	v_mfma_f32_16x16x32_bf16 v[36:39], v[72:75], v[88:91], v[36:39]
	v_mfma_f32_16x16x32_bf16 v[40:43], v[72:75], v[96:99], v[40:43]
	v_mfma_f32_16x16x32_bf16 v[44:47], v[72:75], v[104:107], v[44:47]
	v_mfma_f32_16x16x32_bf16 v[48:51], v[72:75], v[112:115], v[48:51]
	v_mfma_f32_16x16x32_bf16 v[52:55], v[80:83], v[88:91], v[52:55]
	v_mfma_f32_16x16x32_bf16 v[56:59], v[80:83], v[96:99], v[56:59]
	v_mfma_f32_16x16x32_bf16 v[60:63], v[80:83], v[104:107], v[60:63]
	v_mfma_f32_16x16x32_bf16 v[64:67], v[80:83], v[112:115], v[64:67]
	global_load_dwordx4 v[68:71], v[232:233], off offset:384
	global_load_dwordx4 v[76:79], v[234:235], off offset:384
	global_load_dwordx4 v[72:75], v[232:233], off offset:448
	global_load_dwordx4 v[80:83], v[234:235], off offset:448
	global_load_dwordx4 v[84:87], v236, s[46:47] offset:384
	global_load_dwordx4 v[88:91], v236, s[46:47] offset:448
	global_load_dwordx4 v[92:95], v236, s[48:49] offset:384
	global_load_dwordx4 v[96:99], v236, s[48:49] offset:448
	global_load_dwordx4 v[100:103], v236, s[50:51] offset:384
	global_load_dwordx4 v[104:107], v236, s[50:51] offset:448
	global_load_dwordx4 v[108:111], v236, s[52:53] offset:384
	global_load_dwordx4 v[112:115], v236, s[52:53] offset:448
	s_waitcnt vmcnt(24)
; #define GAS __attribute__((address_space(1)))
; __device__ __forceinline__ f32x4 mfma16(const bf16x8& a, const bf16x8& b, const f32x4& c) { return __builtin_amdgcn_mfma_f32_16x16x32_bf16(a, b, c, 0, 0, 0); }
; template <class F> __device__ __forceinline__ void skinny_tile_sk(const GAS bf16* A, int lda, const GAS bf16* Bt, int K, int n0, int wave, int lane, float* red, F&& epi) {
;     const int fr = lane & 15, fq = lane >> 4, kc = K >> 3;
;     const GAS bf16* ap = A + (size_t)fr * lda + wave * kc + fq * 8; const GAS bf16* bp = Bt + (size_t)(n0 + fr) * K + wave * kc + fq * 8;
;     f32x4 acc0 = {0.f, 0.f, 0.f, 0.f}, acc1 = {0.f, 0.f, 0.f, 0.f};
;     for (int k = 0; k < kc; k += 256) { bf16x8 a[8], bb[8];
; #pragma unroll
;         for (int i = 0; i < 8; ++i) { a[i] = *(const GAS bf16x8*)(ap + k + i * 32); bb[i] = *(const GAS bf16x8*)(bp + k + i * 32); }
; #pragma unroll
;         for (int i = 0; i < 8; i += 2) { acc0 = mfma16(a[i], bb[i], acc0); acc1 = mfma16(a[i + 1], bb[i + 1], acc1); } }
;     __syncthreads();
;     *(f32x4*)(red + wave * 256 + lane * 4) = acc0 + acc1;
;     __syncthreads();
;     if (wave == 0) { f32x4 s = {0.f, 0.f, 0.f, 0.f};
; #pragma unroll
;         for (int w = 0; w < 8; ++w) s += *(const f32x4*)(red + w * 256 + lane * 4);
; __device__ __forceinline__ void side_gemm1(const Params& P, int seg) {
;     ...
;             const float t = v * rstd1[r0 + row] + P.dt_bias[col]; dtv[(size_t)(r0 + row) * 64 + col] = (t > 20.f) ? t : log1pf(__expf(t)); }); }
	v_mfma_f32_16x16x32_bf16 v[36:39], v[120:123], v[136:139], v[36:39]
	v_mfma_f32_16x16x32_bf16 v[40:43], v[120:123], v[144:147], v[40:43]
	v_mfma_f32_16x16x32_bf16 v[44:47], v[120:123], v[152:155], v[44:47]
	v_mfma_f32_16x16x32_bf16 v[48:51], v[120:123], v[160:163], v[48:51]
	v_mfma_f32_16x16x32_bf16 v[52:55], v[128:131], v[136:139], v[52:55]
	v_mfma_f32_16x16x32_bf16 v[56:59], v[128:131], v[144:147], v[56:59]
	v_mfma_f32_16x16x32_bf16 v[60:63], v[128:131], v[152:155], v[60:63]
	v_mfma_f32_16x16x32_bf16 v[64:67], v[128:131], v[160:163], v[64:67]
	v_mfma_f32_16x16x32_bf16 v[36:39], v[124:127], v[140:143], v[36:39]
	v_mfma_f32_16x16x32_bf16 v[40:43], v[124:127], v[148:151], v[40:43]
	v_mfma_f32_16x16x32_bf16 v[44:47], v[124:127], v[156:159], v[44:47]
	v_mfma_f32_16x16x32_bf16 v[48:51], v[124:127], v[164:167], v[48:51]
	v_mfma_f32_16x16x32_bf16 v[52:55], v[132:135], v[140:143], v[52:55]
	v_mfma_f32_16x16x32_bf16 v[56:59], v[132:135], v[148:151], v[56:59]
	v_mfma_f32_16x16x32_bf16 v[60:63], v[132:135], v[156:159], v[60:63]
	v_mfma_f32_16x16x32_bf16 v[64:67], v[132:135], v[164:167], v[64:67]
	s_waitcnt vmcnt(12)
	v_mfma_f32_16x16x32_bf16 v[36:39], v[184:187], v[200:203], v[36:39]
	v_mfma_f32_16x16x32_bf16 v[40:43], v[184:187], v[208:211], v[40:43]
	v_mfma_f32_16x16x32_bf16 v[44:47], v[184:187], v[216:219], v[44:47]
	v_mfma_f32_16x16x32_bf16 v[48:51], v[184:187], v[224:227], v[48:51]
	v_mfma_f32_16x16x32_bf16 v[52:55], v[192:195], v[200:203], v[52:55]
	v_mfma_f32_16x16x32_bf16 v[56:59], v[192:195], v[208:211], v[56:59]
	v_mfma_f32_16x16x32_bf16 v[60:63], v[192:195], v[216:219], v[60:63]
	v_mfma_f32_16x16x32_bf16 v[64:67], v[192:195], v[224:227], v[64:67]
	v_mfma_f32_16x16x32_bf16 v[36:39], v[188:191], v[204:207], v[36:39]
	v_mfma_f32_16x16x32_bf16 v[40:43], v[188:191], v[212:215], v[40:43]
	v_mfma_f32_16x16x32_bf16 v[44:47], v[188:191], v[220:223], v[44:47]
	v_mfma_f32_16x16x32_bf16 v[48:51], v[188:191], v[228:231], v[48:51]
	v_mfma_f32_16x16x32_bf16 v[52:55], v[196:199], v[204:207], v[52:55]
	v_mfma_f32_16x16x32_bf16 v[56:59], v[196:199], v[212:215], v[56:59]
	v_mfma_f32_16x16x32_bf16 v[60:63], v[196:199], v[220:223], v[60:63]
	v_mfma_f32_16x16x32_bf16 v[64:67], v[196:199], v[228:231], v[64:67]
	s_waitcnt vmcnt(0)
	v_mfma_f32_16x16x32_bf16 v[36:39], v[68:71], v[84:87], v[36:39]
	v_mfma_f32_16x16x32_bf16 v[40:43], v[68:71], v[92:95], v[40:43]
	v_mfma_f32_16x16x32_bf16 v[44:47], v[68:71], v[100:103], v[44:47]
	v_mfma_f32_16x16x32_bf16 v[48:51], v[68:71], v[108:111], v[48:51]
	v_mfma_f32_16x16x32_bf16 v[52:55], v[76:79], v[84:87], v[52:55]
	v_mfma_f32_16x16x32_bf16 v[56:59], v[76:79], v[92:95], v[56:59]
	v_mfma_f32_16x16x32_bf16 v[60:63], v[76:79], v[100:103], v[60:63]
	v_mfma_f32_16x16x32_bf16 v[64:67], v[76:79], v[108:111], v[64:67]
	v_mfma_f32_16x16x32_bf16 v[36:39], v[72:75], v[88:91], v[36:39]
	v_mfma_f32_16x16x32_bf16 v[40:43], v[72:75], v[96:99], v[40:43]
	v_mfma_f32_16x16x32_bf16 v[44:47], v[72:75], v[104:107], v[44:47]
	v_mfma_f32_16x16x32_bf16 v[48:51], v[72:75], v[112:115], v[48:51]
	v_mfma_f32_16x16x32_bf16 v[52:55], v[80:83], v[88:91], v[52:55]
	v_mfma_f32_16x16x32_bf16 v[56:59], v[80:83], v[96:99], v[56:59]
	v_mfma_f32_16x16x32_bf16 v[60:63], v[80:83], v[104:107], v[60:63]
	v_mfma_f32_16x16x32_bf16 v[64:67], v[80:83], v[112:115], v[64:67]
	v_and_b32_e32 v18, 63, v172
	v_lshlrev_b32_e32 v18, 4, v18
	v_lshrrev_b32_e32 v19, 2, v116
	v_lshl_add_u32 v220, v116, 10, v18
	v_lshl_add_u32 v221, v19, 15, v220
	v_xor_b32_e32 v222, 1, v19
	v_lshl_add_u32 v222, v222, 15, v220
	s_nop 7
	ds_write_b128 v221, v[36:39] offset:0
	ds_write_b128 v222, v[52:55] offset:0
	ds_write_b128 v221, v[40:43] offset:8192
	ds_write_b128 v222, v[56:59] offset:8192
	ds_write_b128 v221, v[44:47] offset:16384
	ds_write_b128 v222, v[60:63] offset:16384
	ds_write_b128 v221, v[48:51] offset:24576
	ds_write_b128 v222, v[64:67] offset:24576
	s_waitcnt lgkmcnt(0)
	s_barrier
	v_lshl_add_u32 v19, v19, 2, v117
	v_lshl_add_u32 v19, v19, 13, v18
	ds_read_b128 v[68:71], v19 offset:0
	ds_read_b128 v[72:75], v19 offset:1024
	ds_read_b128 v[76:79], v19 offset:2048
	ds_read_b128 v[80:83], v19 offset:3072
	ds_read_b128 v[84:87], v19 offset:4096
	ds_read_b128 v[88:91], v19 offset:5120
	ds_read_b128 v[92:95], v19 offset:6144
	ds_read_b128 v[96:99], v19 offset:7168
	s_waitcnt lgkmcnt(0)
	v_add_f32_e32 v68, v68, v72
	v_add_f32_e32 v76, v76, v80
	v_add_f32_e32 v84, v84, v88
	v_add_f32_e32 v92, v92, v96
	v_add_f32_e32 v69, v69, v73
	v_add_f32_e32 v77, v77, v81
	v_add_f32_e32 v85, v85, v89
	v_add_f32_e32 v93, v93, v97
	v_add_f32_e32 v70, v70, v74
	v_add_f32_e32 v78, v78, v82
	v_add_f32_e32 v86, v86, v90
	v_add_f32_e32 v94, v94, v98
	v_add_f32_e32 v71, v71, v75
	v_add_f32_e32 v79, v79, v83
	v_add_f32_e32 v87, v87, v91
	v_add_f32_e32 v95, v95, v99
	v_add_f32_e32 v68, v68, v76
	v_add_f32_e32 v84, v84, v92
	v_add_f32_e32 v69, v69, v77
	v_add_f32_e32 v85, v85, v93
	v_add_f32_e32 v70, v70, v78
	v_add_f32_e32 v86, v86, v94
	v_add_f32_e32 v71, v71, v79
	v_add_f32_e32 v87, v87, v95
	v_add_f32_e32 v4, v68, v84
	v_add_f32_e32 v5, v69, v85
	v_add_f32_e32 v6, v70, v86
	v_add_f32_e32 v7, v71, v87
	v_mov_b32_e32 v8, 0
	v_mov_b32_e32 v9, 0
	v_mov_b32_e32 v10, 0
	v_mov_b32_e32 v11, 0
	s_mov_b32 s100, 0
	v_mov_b32_e32 v8, v243
	v_mov_b32_e32 v32, v244
	v_mov_b32_e32 v216, v245
	v_mov_b32_e32 v217, v246
	v_mov_b32_e32 v218, v247
	v_lshl_add_u64 v[18:19], v[16:17], 2, s[14:15]
	s_branch .Lsg1_join2

; __device__ __forceinline__ void side_gemm1(const Params& P, int seg) {
;     ...
;             const float t = v * rstd1[r0 + row] + P.dt_bias[col]; dtv[(size_t)(r0 + row) * 64 + col] = (t > 20.f) ? t : log1pf(__expf(t)); }); }
.Lsg1_join2:
	s_waitcnt vmcnt(0)
	v_mov_b32_e32 v219, v32
	v_fmac_f32_e32 v32, v8, v4
	v_cmp_nlt_f32_e32 vcc, s28, v32
	s_and_saveexec_b64 s[26:27], vcc
	s_cbranch_execz .LBB0_98
	v_mul_f32_e32 v4, 0x3fb8aa3b, v32
	v_exp_f32_e32 v4, v4
	s_nop 0
	v_add_f32_e32 v8, 1.0, v4
	v_frexp_mant_f32_e32 v23, v8
	v_cvt_f64_f32_e32 v[20:21], v8
	v_add_f32_e32 v22, -1.0, v8
	v_frexp_exp_i32_f64_e32 v20, v[20:21]
	v_cmp_gt_f32_e32 vcc, s29, v23
	v_sub_f32_e32 v32, v22, v8
	v_sub_f32_e32 v22, v4, v22
	v_subbrev_co_u32_e32 v36, vcc, 0, v20, vcc
	v_add_f32_e32 v32, 1.0, v32
	v_sub_u32_e32 v20, 0, v36
	v_add_f32_e32 v22, v22, v32
	v_ldexp_f32 v8, v8, v20
	v_ldexp_f32 v20, v22, v20
	v_add_f32_e32 v22, -1.0, v8
	v_add_f32_e32 v21, 1.0, v22
	v_sub_f32_e32 v21, v8, v21
	v_add_f32_e32 v23, v20, v21
	v_add_f32_e32 v21, 1.0, v8
	v_add_f32_e32 v32, -1.0, v21
	v_sub_f32_e32 v8, v8, v32
	v_add_f32_e32 v8, v20, v8
	v_add_f32_e32 v37, v21, v8
	v_rcp_f32_e32 v38, v37
	v_sub_f32_e32 v20, v37, v21
	v_add_f32_e32 v21, v22, v23
	v_sub_f32_e32 v8, v8, v20
	v_mul_f32_e32 v40, v21, v38
	v_sub_f32_e32 v20, v21, v22
	v_mul_f32_e32 v22, v37, v40
	v_fma_f32 v32, v40, v37, -v22
	v_fmac_f32_e32 v32, v40, v8
	v_sub_f32_e32 v39, v23, v20
	v_add_f32_e32 v20, v22, v32
	v_sub_f32_e32 v23, v21, v20
	v_pk_add_f32 v[34:35], v[20:21], v[22:23] neg_lo:[0,1] neg_hi:[0,1]
	v_mov_b32_e32 v33, v20
	v_pk_add_f32 v[20:21], v[34:35], v[32:33] neg_lo:[0,1] neg_hi:[0,1]
	v_cmp_neq_f32_e32 vcc, s31, v4
	v_add_f32_e32 v21, v39, v21
	v_add_f32_e32 v20, v20, v21
	v_add_f32_e32 v21, v23, v20
	v_mul_f32_e32 v39, v38, v21
	v_mul_f32_e32 v22, v37, v39
	v_fma_f32 v32, v39, v37, -v22
	v_fmac_f32_e32 v32, v39, v8
	v_sub_f32_e32 v8, v23, v21
	v_add_f32_e32 v8, v20, v8
	v_add_f32_e32 v20, v22, v32
	v_sub_f32_e32 v23, v21, v20
	v_pk_add_f32 v[34:35], v[20:21], v[22:23] neg_lo:[0,1] neg_hi:[0,1]
	v_mov_b32_e32 v33, v20
	v_pk_add_f32 v[20:21], v[34:35], v[32:33] neg_lo:[0,1] neg_hi:[0,1]
	s_nop 0
	v_add_f32_e32 v8, v8, v21
	v_add_f32_e32 v8, v20, v8
	v_add_f32_e32 v21, v40, v39
	v_add_f32_e32 v8, v23, v8
	v_sub_f32_e32 v20, v21, v40
	v_mul_f32_e32 v8, v38, v8
	v_sub_f32_e32 v20, v39, v20
	v_add_f32_e32 v8, v20, v8
	v_add_f32_e32 v22, v21, v8
	v_mul_f32_e32 v32, v22, v22
	v_fmamk_f32 v20, v32, 0x3e9b6dac, v177
	v_fmaak_f32 v179, v32, v20, 0x3f2aaada
	v_cvt_f32_i32_e32 v20, v36
	v_sub_f32_e32 v21, v22, v21
	v_sub_f32_e32 v8, v8, v21
	v_mul_f32_e32 v21, v22, v32
	v_pk_mul_f32 v[32:33], v[20:21], v[178:179]
	v_ldexp_f32 v23, v22, 1
	v_fma_f32 v22, v20, s30, -v32
	v_fmac_f32_e32 v22, 0xb102e308, v20
	v_pk_add_f32 v[20:21], v[32:33], v[22:23]
	v_ldexp_f32 v8, v8, 1
	v_sub_f32_e32 v23, v21, v23
	v_sub_f32_e32 v23, v33, v23
	v_add_f32_e32 v35, v8, v23
	v_mov_b32_e32 v34, v32
	v_pk_add_f32 v[32:33], v[20:21], v[32:33] neg_lo:[0,1] neg_hi:[0,1]
	v_pk_add_f32 v[36:37], v[20:21], v[34:35]
	v_mov_b32_e32 v23, v20
	v_mov_b32_e32 v33, v37
	v_pk_add_f32 v[38:39], v[22:23], v[32:33] neg_lo:[0,1] neg_hi:[0,1]
	v_pk_add_f32 v[22:23], v[22:23], v[32:33]
	v_mov_b32_e32 v34, v35
	v_pk_add_f32 v[32:33], v[22:23], v[20:21] op_sel:[1,0] op_sel_hi:[0,1] neg_lo:[0,1] neg_hi:[0,1]
	v_pk_add_f32 v[40:41], v[36:37], v[32:33] op_sel_hi:[1,0] neg_lo:[0,1] neg_hi:[0,1]
	v_mov_b32_e32 v36, v37
	v_mov_b32_e32 v37, v23
	v_pk_mov_b32 v[32:33], v[20:21], v[32:33] op_sel:[1,0]
	v_mov_b32_e32 v35, v20
	v_pk_add_f32 v[32:33], v[36:37], v[32:33] neg_lo:[0,1] neg_hi:[0,1]
	v_mov_b32_e32 v40, v38
	v_pk_add_f32 v[20:21], v[34:35], v[32:33] neg_lo:[0,1] neg_hi:[0,1]
	v_mov_b32_e32 v39, v23
	v_pk_add_f32 v[32:33], v[40:41], v[20:21]
	s_nop 0
	v_pk_add_f32 v[34:35], v[32:33], v[32:33] op_sel:[0,1] op_sel_hi:[1,0]
	s_nop 0
	v_pk_add_f32 v[22:23], v[22:23], v[34:35] op_sel:[1,0] op_sel_hi:[0,1]
	v_mov_b32_e32 v33, v22
	v_pk_add_f32 v[36:37], v[32:33], v[38:39] neg_lo:[0,1] neg_hi:[0,1]
	v_mov_b32_e32 v21, v34
	v_sub_f32_e32 v8, v32, v36
	v_pk_add_f32 v[20:21], v[20:21], v[36:37] neg_lo:[0,1] neg_hi:[0,1]
	v_sub_f32_e32 v8, v38, v8
	v_add_f32_e32 v8, v20, v8
	v_add_f32_e32 v8, v8, v21
	v_add_f32_e32 v8, v22, v8
	v_cndmask_b32_e32 v8, v240, v8, vcc
	v_cmp_ngt_f32_e32 vcc, -1.0, v4
	s_nop 1
	v_cndmask_b32_e32 v8, v241, v8, vcc
	v_cmp_neq_f32_e32 vcc, -1.0, v4
	s_nop 1
	v_cndmask_b32_e32 v8, v242, v8, vcc
	v_cmp_lt_f32_e64 vcc, |v4|, s38
	s_nop 1
	v_cndmask_b32_e32 v32, v8, v4, vcc
